# P6 out-proj K-loop: same 2-set ping-pong / rotated-barrier structure as P2
# speedup vs baseline: 1.0180x; 1.0058x over previous
; DI unsigned pk_bf16(float lo, float hi) { f32x2v v = {lo, hi}; bf16x2v b = __builtin_convertvector(v, bf16x2v); return __builtin_bit_cast(unsigned, b); }
; DI int tid_() { int t = threadIdx.x; asm volatile("" : "+v"(t)); return t; }
; DI void lds_sync() { wait_lgkm0(); bar_(); }
; DI void phase6(const Params& p, char* smem) {
;     ...
;     const int tc_ = tid_();
;     const int ch = tc_ & 63, r0 = tc_ >> 6;
;     const float4 g = *(const float4*)(p.mod + (tokTile >> 3) * 6144 + 2048 + nt * 256 + ch * 4);
; #pragma unroll
;     for (int tn = 0; tn < 2; ++tn) {
;       const size_t obase = ((size_t)tokTile * 256 + tn * 32) * DM + nt * 256 + ch * 4;
; #pragma unroll
;       for (int tm = 0; tm < 4; ++tm) {
;         char* d = smem + (wn * 32 + r) * 1040 + (wm * 128 + tm * 32 + 4 * hh) * 4;
; #pragma unroll
;         for (int q = 0; q < 4; ++q) *(float4*)(d + 32 * q) = make_float4(acc[tm][tn][4 * q], acc[tm][tn][4 * q + 1], acc[tm][tn][4 * q + 2], acc[tm][tn][4 * q + 3]);
;       }
;       lds_sync();
; #pragma unroll
;       for (int hb = 0; hb < 2; ++hb) {
;         float4 xv[8];
; #pragma unroll
;         for (int i = 0; i < 8; ++i) {
;           const int row = r0 + 8 * (hb * 8 + i);
;           xv[i] = *(const float4*)(p.x + obase + (size_t)((row >> 5) * 64 + (row & 31)) * DM);
;         }
; #pragma unroll
;         for (int i = 0; i < 8; ++i) {
;           const int row = r0 + 8 * (hb * 8 + i);
;           const float4 a = *(const float4*)(smem + row * 1040 + ch * 16);
;           uint2 ob; ob.x = pk_bf16(xv[i].x + g.x * a.x, xv[i].y + g.y * a.y); ob.y = pk_bf16(xv[i].z + g.z * a.z, xv[i].w + g.w * a.w);
;           *(uint2*)(p.x1b + obase + (size_t)((row >> 5) * 64 + (row & 31)) * DM) = ob;
;         }
.Lp6_cont:
	s_setprio 0
	s_lshr_b32 s4, s44, 3
	s_mulk_i32 s4, 0x6000
	s_add_u32 s4, s14, s4
	v_mov_b32_e32 v128, v220
	s_addc_u32 s5, s15, 0
	s_lshl_b32 s7, s43, 8
	s_lshl_b32 s8, s43, 10
	s_waitcnt lgkmcnt(0)
	s_barrier
	s_add_u32 s4, s4, s8
	v_and_b32_e32 v129, 63, v128
	s_addc_u32 s5, s5, 0
	v_lshlrev_b32_e32 v184, 4, v129
	v_ashrrev_i32_e32 v132, 6, v128
	v_lshl_add_u64 v[130:131], s[4:5], 0, v[184:185]
	s_or_b32 s4, s6, s7
	v_lshl_or_b32 v136, v129, 2, s4
	v_mad_u64_u32 v[128:129], s[4:5], v132, s34, v[184:185]
	v_and_b32_e32 v137, 31, v132
	v_lshlrev_b32_e32 v129, 1, v132
	s_waitcnt vmcnt(0)
	ds_write_b128 v202, v[112:115]
	ds_write_b128 v202, v[116:119] offset:32
	ds_write_b128 v202, v[120:123] offset:64
	ds_write_b128 v202, v[124:127] offset:96
	ds_write_b128 v202, v[96:99] offset:128
	ds_write_b128 v202, v[100:103] offset:160
	ds_write_b128 v202, v[104:107] offset:192
	ds_write_b128 v202, v[108:111] offset:224
	ds_write_b128 v202, v[80:83] offset:256
	ds_write_b128 v202, v[84:87] offset:288
	ds_write_b128 v202, v[88:91] offset:320
	ds_write_b128 v202, v[92:95] offset:352
	ds_write_b128 v202, v[64:67] offset:384
	ds_write_b128 v202, v[68:71] offset:416
	ds_write_b128 v202, v[72:75] offset:448
	ds_write_b128 v202, v[76:79] offset:480
	v_and_or_b32 v126, v129, s41, v137
	v_lshlrev_b32_e32 v184, 2, v136
	v_ashrrev_i32_e32 v127, 31, v126
	v_lshl_add_u64 v[116:117], s[16:17], 0, v[184:185]
	v_lshlrev_b64 v[68:69], 12, v[126:127]
	v_add_co_u32_e32 v64, vcc, s38, v130
	v_add_u32_e32 v133, 8, v132
	v_lshl_add_u64 v[70:71], v[116:117], 0, v[68:69]
	v_addc_co_u32_e32 v65, vcc, 0, v131, vcc
	global_load_dwordx4 v[64:67], v[64:65], off
	s_waitcnt lgkmcnt(0)
	s_barrier
	global_load_dwordx4 v[84:87], v[70:71], off
	v_and_b32_e32 v150, 31, v133
	v_lshlrev_b32_e32 v70, 1, v133
	v_and_or_b32 v130, v70, s41, v150
	v_ashrrev_i32_e32 v131, 31, v130
	v_lshlrev_b64 v[70:71], 12, v[130:131]
	v_lshl_add_u64 v[72:73], v[116:117], 0, v[70:71]
	v_bitop3_b32 v151, v132, 16, 31 bitop3:0x6c
	global_load_dwordx4 v[88:91], v[72:73], off
	v_add_u32_e32 v72, 32, v129
	v_add_u32_e32 v76, 24, v132
	v_and_or_b32 v132, v72, s41, v151
	v_ashrrev_i32_e32 v133, 31, v132
	v_lshlrev_b64 v[72:73], 12, v[132:133]
	v_lshl_add_u64 v[74:75], v[116:117], 0, v[72:73]
	v_and_b32_e32 v154, 31, v76
	global_load_dwordx4 v[92:95], v[74:75], off
	v_lshlrev_b32_e32 v74, 1, v76
	v_and_or_b32 v138, v74, s41, v154
	v_ashrrev_i32_e32 v139, 31, v138
	v_lshlrev_b64 v[74:75], 12, v[138:139]
	v_lshl_add_u64 v[76:77], v[116:117], 0, v[74:75]
	global_load_dwordx4 v[96:99], v[76:77], off
	v_add_u32_e32 v76, 64, v129
	v_and_or_b32 v140, v76, s41, v137
	v_ashrrev_i32_e32 v141, 31, v140
	v_lshlrev_b64 v[76:77], 12, v[140:141]
	v_lshl_add_u64 v[78:79], v[116:117], 0, v[76:77]
	global_load_dwordx4 v[100:103], v[78:79], off
	v_add_u32_e32 v78, 0x50, v129
	v_and_or_b32 v142, v78, s41, v150
	v_ashrrev_i32_e32 v143, 31, v142
	v_lshlrev_b64 v[78:79], 12, v[142:143]
	v_lshl_add_u64 v[80:81], v[116:117], 0, v[78:79]
	global_load_dwordx4 v[104:107], v[80:81], off
	v_add_u32_e32 v80, 0x60, v129
	v_and_or_b32 v144, v80, s41, v151
	v_ashrrev_i32_e32 v145, 31, v144
	v_lshlrev_b64 v[80:81], 12, v[144:145]
	v_lshl_add_u64 v[82:83], v[116:117], 0, v[80:81]
	global_load_dwordx4 v[108:111], v[82:83], off
	v_add_u32_e32 v82, 0x70, v129
	v_and_or_b32 v146, v82, s41, v154
	v_ashrrev_i32_e32 v147, 31, v146
	v_lshlrev_b64 v[82:83], 12, v[146:147]
	v_lshl_add_u64 v[112:113], v[116:117], 0, v[82:83]
	global_load_dwordx4 v[112:115], v[112:113], off
	ds_read_b128 v[118:121], v128
	ds_read_b128 v[122:125], v128 offset:8320
	v_lshlrev_b32_e32 v184, 1, v136
	v_lshl_add_u64 v[134:135], s[18:19], 0, v[184:185]
	v_add_u32_e32 v186, 0x6180, v128
	v_add_u32_e32 v187, 0x8200, v128
	v_add_u32_e32 v188, 0xa280, v128
	v_add_u32_e32 v189, 0xc300, v128
	v_add_u32_e32 v190, 0xe380, v128
	s_add_i32 s42, s42, s95
	s_add_i32 s31, s31, s95
	s_cmpk_lt_u32 s42, 0x80
	s_waitcnt vmcnt(7) lgkmcnt(1)
	v_pk_fma_f32 v[84:85], v[64:65], v[118:119], v[84:85]
	s_nop 0
	v_cvt_pk_bf16_f32 v148, v84, v85
	v_pk_fma_f32 v[84:85], v[66:67], v[120:121], v[86:87]
	ds_read_b128 v[118:121], v128 offset:24960
	v_cvt_pk_bf16_f32 v149, v84, v85
	v_lshlrev_b64 v[84:85], 11, v[126:127]
	v_lshl_add_u64 v[126:127], v[134:135], 0, v[84:85]
	s_waitcnt vmcnt(6) lgkmcnt(1)
	v_pk_fma_f32 v[86:87], v[64:65], v[122:123], v[88:89]
	s_nop 0
	v_cvt_pk_bf16_f32 v122, v86, v87
	v_pk_fma_f32 v[86:87], v[66:67], v[124:125], v[90:91]
	ds_read_b128 v[88:91], v128 offset:16640
	v_cvt_pk_bf16_f32 v123, v86, v87
	v_lshlrev_b64 v[86:87], 11, v[130:131]
	v_lshl_add_u64 v[124:125], v[134:135], 0, v[86:87]
	s_waitcnt vmcnt(5) lgkmcnt(0)
	v_pk_fma_f32 v[88:89], v[64:65], v[88:89], v[92:93]
	s_nop 0
	v_cvt_pk_bf16_f32 v130, v88, v89
	v_pk_fma_f32 v[88:89], v[66:67], v[90:91], v[94:95]
	ds_read_b128 v[92:95], v128 offset:33280
	v_cvt_pk_bf16_f32 v131, v88, v89
	v_lshlrev_b64 v[88:89], 11, v[132:133]
	s_waitcnt vmcnt(4)
	v_pk_fma_f32 v[90:91], v[64:65], v[118:119], v[96:97]
	v_lshl_add_u64 v[132:133], v[134:135], 0, v[88:89]
	v_cvt_pk_bf16_f32 v118, v90, v91
	v_pk_fma_f32 v[90:91], v[66:67], v[120:121], v[98:99]
	ds_read_b128 v[96:99], v128 offset:41600
	v_cvt_pk_bf16_f32 v119, v90, v91
	s_waitcnt vmcnt(3) lgkmcnt(1)
	v_pk_fma_f32 v[92:93], v[64:65], v[92:93], v[100:101]
	v_lshlrev_b64 v[90:91], 11, v[138:139]
	v_cvt_pk_bf16_f32 v138, v92, v93
	v_pk_fma_f32 v[92:93], v[66:67], v[94:95], v[102:103]
	ds_read_b128 v[100:103], v128 offset:58240
	v_cvt_pk_bf16_f32 v139, v92, v93
	s_waitcnt vmcnt(2) lgkmcnt(1)
; DI unsigned pk_bf16(float lo, float hi) { f32x2v v = {lo, hi}; bf16x2v b = __builtin_convertvector(v, bf16x2v); return __builtin_bit_cast(unsigned, b); }
; DI void lds_sync() { wait_lgkm0(); bar_(); }
; DI void phase6(const Params& p, char* smem) {
;     ...
;       for (int hb = 0; hb < 2; ++hb) {
;         float4 xv[8];
; #pragma unroll
;         for (int i = 0; i < 8; ++i) {
;           const int row = r0 + 8 * (hb * 8 + i);
;           xv[i] = *(const float4*)(p.x + obase + (size_t)((row >> 5) * 64 + (row & 31)) * DM);
;         }
; #pragma unroll
;         for (int i = 0; i < 8; ++i) {
;           const int row = r0 + 8 * (hb * 8 + i);
;           const float4 a = *(const float4*)(smem + row * 1040 + ch * 16);
;           uint2 ob; ob.x = pk_bf16(xv[i].x + g.x * a.x, xv[i].y + g.y * a.y); ob.y = pk_bf16(xv[i].z + g.z * a.z, xv[i].w + g.w * a.w);
;           *(uint2*)(p.x1b + obase + (size_t)((row >> 5) * 64 + (row & 31)) * DM) = ob;
;         }
;       }
;       lds_sync();
	v_pk_fma_f32 v[94:95], v[64:65], v[96:97], v[104:105]
	v_lshlrev_b64 v[92:93], 11, v[140:141]
	v_cvt_pk_bf16_f32 v104, v94, v95
	v_pk_fma_f32 v[94:95], v[66:67], v[98:99], v[106:107]
	ds_read_b128 v[96:99], v128 offset:49920
	v_cvt_pk_bf16_f32 v105, v94, v95
	v_lshlrev_b64 v[94:95], 11, v[142:143]
	v_lshl_add_u64 v[120:121], v[134:135], 0, v[90:91]
	v_lshl_add_u64 v[140:141], v[134:135], 0, v[92:93]
	s_waitcnt vmcnt(1) lgkmcnt(0)
	v_pk_fma_f32 v[96:97], v[64:65], v[96:97], v[108:109]
	v_lshl_add_u64 v[106:107], v[134:135], 0, v[94:95]
	v_cvt_pk_bf16_f32 v108, v96, v97
	v_pk_fma_f32 v[96:97], v[66:67], v[98:99], v[110:111]
	s_waitcnt vmcnt(0)
	v_pk_fma_f32 v[100:101], v[64:65], v[100:101], v[112:113]
	v_cvt_pk_bf16_f32 v109, v96, v97
	v_lshlrev_b64 v[96:97], 11, v[144:145]
	v_lshl_add_u64 v[98:99], v[134:135], 0, v[96:97]
	global_store_dwordx2 v[126:127], v[148:149], off
	global_store_dwordx2 v[124:125], v[122:123], off
	global_store_dwordx2 v[132:133], v[130:131], off
	global_store_dwordx2 v[120:121], v[118:119], off
	global_store_dwordx2 v[140:141], v[138:139], off
	global_store_dwordx2 v[106:107], v[104:105], off
	global_store_dwordx2 v[98:99], v[108:109], off
	v_pk_fma_f32 v[98:99], v[66:67], v[102:103], v[114:115]
	v_cvt_pk_bf16_f32 v100, v100, v101
	v_cvt_pk_bf16_f32 v101, v98, v99
	v_lshlrev_b64 v[98:99], 11, v[146:147]
	v_lshl_add_u64 v[102:103], v[134:135], 0, v[98:99]
	global_store_dwordx2 v[102:103], v[100:101], off
	v_add_u32_e32 v100, 0x80, v129
	v_and_or_b32 v126, v100, s41, v137
	v_ashrrev_i32_e32 v127, 31, v126
	v_lshlrev_b64 v[100:101], 12, v[126:127]
	v_lshl_add_u64 v[102:103], v[116:117], 0, v[100:101]
	global_load_dwordx4 v[118:121], v[102:103], off
	v_add_u32_e32 v102, 0x90, v129
	v_and_or_b32 v162, v102, s41, v150
	v_ashrrev_i32_e32 v163, 31, v162
	v_lshlrev_b64 v[102:103], 12, v[162:163]
	v_lshl_add_u64 v[104:105], v[116:117], 0, v[102:103]
	global_load_dwordx4 v[122:125], v[104:105], off
	v_add_u32_e32 v104, 0xa0, v129
	v_and_or_b32 v164, v104, s41, v151
	v_ashrrev_i32_e32 v165, 31, v164
	v_lshlrev_b64 v[104:105], 12, v[164:165]
	v_lshl_add_u64 v[106:107], v[116:117], 0, v[104:105]
	global_load_dwordx4 v[130:133], v[106:107], off
	v_add_u32_e32 v106, 0xb0, v129
	v_and_or_b32 v166, v106, s41, v154
	v_ashrrev_i32_e32 v167, 31, v166
	v_lshlrev_b64 v[106:107], 12, v[166:167]
	v_lshl_add_u64 v[108:109], v[116:117], 0, v[106:107]
	global_load_dwordx4 v[138:141], v[108:109], off
	v_add_u32_e32 v108, 0xc0, v129
	v_and_or_b32 v168, v108, s41, v137
	v_ashrrev_i32_e32 v169, 31, v168
	v_lshlrev_b64 v[108:109], 12, v[168:169]
	v_lshl_add_u64 v[110:111], v[116:117], 0, v[108:109]
	global_load_dwordx4 v[142:145], v[110:111], off
	v_add_u32_e32 v110, 0xd0, v129
	v_and_or_b32 v170, v110, s41, v150
	v_ashrrev_i32_e32 v171, 31, v170
	v_lshlrev_b64 v[110:111], 12, v[170:171]
	v_lshl_add_u64 v[112:113], v[116:117], 0, v[110:111]
	global_load_dwordx4 v[146:149], v[112:113], off
	v_add_u32_e32 v112, 0xe0, v129
	v_and_or_b32 v172, v112, s41, v151
	v_ashrrev_i32_e32 v173, 31, v172
	v_lshlrev_b64 v[112:113], 12, v[172:173]
	v_lshl_add_u64 v[114:115], v[116:117], 0, v[112:113]
	global_load_dwordx4 v[150:153], v[114:115], off
	v_add_u32_e32 v114, 0xf0, v129
	v_and_or_b32 v174, v114, s41, v154
	v_ashrrev_i32_e32 v175, 31, v174
	v_lshlrev_b64 v[114:115], 12, v[174:175]
	v_lshl_add_u64 v[116:117], v[116:117], 0, v[114:115]
	global_load_dwordx4 v[154:157], v[116:117], off
	v_add_u32_e32 v129, 0x10400, v128
	ds_read_b128 v[158:161], v129
	v_add_u32_e32 v137, 0x4100, v128
	v_add_u32_e32 v191, 0xe380, v137
	s_waitcnt vmcnt(7) lgkmcnt(0)
	v_pk_fma_f32 v[116:117], v[64:65], v[158:159], v[118:119]
	s_nop 0
	v_cvt_pk_bf16_f32 v176, v116, v117
	v_pk_fma_f32 v[116:117], v[66:67], v[160:161], v[120:121]
	ds_read_b128 v[118:121], v137 offset:58240
	ds_read_b128 v[158:161], v186 offset:58240
	v_cvt_pk_bf16_f32 v177, v116, v117
	v_lshlrev_b64 v[116:117], 11, v[126:127]
	v_lshl_add_u64 v[178:179], v[134:135], 0, v[116:117]
	s_waitcnt vmcnt(6) lgkmcnt(1)
	v_pk_fma_f32 v[118:119], v[64:65], v[118:119], v[122:123]
	s_nop 0
	v_cvt_pk_bf16_f32 v180, v118, v119
	v_pk_fma_f32 v[118:119], v[66:67], v[120:121], v[124:125]
	s_waitcnt vmcnt(5) lgkmcnt(0)
	v_pk_fma_f32 v[120:121], v[64:65], v[158:159], v[130:131]
	ds_read_b128 v[122:125], v187 offset:58240
	v_cvt_pk_bf16_f32 v158, v120, v121
	v_pk_fma_f32 v[120:121], v[66:67], v[160:161], v[132:133]
	ds_read_b128 v[130:133], v188 offset:58240
	v_cvt_pk_bf16_f32 v159, v120, v121
	s_waitcnt vmcnt(4) lgkmcnt(1)
	v_pk_fma_f32 v[122:123], v[64:65], v[122:123], v[138:139]
	v_lshlrev_b64 v[120:121], 11, v[164:165]
	v_cvt_pk_bf16_f32 v164, v122, v123
	v_pk_fma_f32 v[122:123], v[66:67], v[124:125], v[140:141]
	ds_read_b128 v[138:141], v190 offset:58240
	v_cvt_pk_bf16_f32 v181, v118, v119
	s_waitcnt vmcnt(3) lgkmcnt(1)
	v_pk_fma_f32 v[124:125], v[64:65], v[130:131], v[142:143]
	v_lshlrev_b64 v[118:119], 11, v[162:163]
	v_cvt_pk_bf16_f32 v182, v124, v125
	v_pk_fma_f32 v[124:125], v[66:67], v[132:133], v[144:145]
	ds_read_b128 v[130:133], v189 offset:58240
	ds_read_b128 v[142:145], v191 offset:49920
	v_cvt_pk_bf16_f32 v165, v122, v123
	v_lshlrev_b64 v[122:123], 11, v[166:167]
	v_cvt_pk_bf16_f32 v183, v124, v125
	s_waitcnt vmcnt(2) lgkmcnt(1)
	v_pk_fma_f32 v[126:127], v[64:65], v[130:131], v[146:147]
	v_lshlrev_b64 v[124:125], 11, v[168:169]
	v_cvt_pk_bf16_f32 v146, v126, v127
	v_pk_fma_f32 v[126:127], v[66:67], v[132:133], v[148:149]
	s_waitcnt vmcnt(1)
	v_pk_fma_f32 v[130:131], v[64:65], v[138:139], v[150:151]
	v_cvt_pk_bf16_f32 v147, v126, v127
	v_lshlrev_b64 v[126:127], 11, v[170:171]
	v_cvt_pk_bf16_f32 v138, v130, v131
	v_pk_fma_f32 v[130:131], v[66:67], v[140:141], v[152:153]
	v_lshl_add_u64 v[132:133], v[134:135], 0, v[126:127]
	v_cvt_pk_bf16_f32 v139, v130, v131
	v_lshlrev_b64 v[130:131], 11, v[172:173]
	v_lshl_add_u64 v[162:163], v[134:135], 0, v[118:119]
	v_lshl_add_u64 v[160:161], v[134:135], 0, v[120:121]
	v_lshl_add_u64 v[166:167], v[134:135], 0, v[122:123]
	v_lshl_add_u64 v[168:169], v[134:135], 0, v[124:125]
	v_lshl_add_u64 v[140:141], v[134:135], 0, v[130:131]
	s_waitcnt vmcnt(0) lgkmcnt(0)
	v_pk_fma_f32 v[142:143], v[64:65], v[142:143], v[154:155]
	global_store_dwordx2 v[178:179], v[176:177], off
	global_store_dwordx2 v[162:163], v[180:181], off
	global_store_dwordx2 v[160:161], v[158:159], off
	global_store_dwordx2 v[166:167], v[164:165], off
	global_store_dwordx2 v[168:169], v[182:183], off
	global_store_dwordx2 v[132:133], v[146:147], off
	global_store_dwordx2 v[140:141], v[138:139], off
	v_pk_fma_f32 v[132:133], v[66:67], v[144:145], v[156:157]
	v_cvt_pk_bf16_f32 v142, v142, v143
	v_cvt_pk_bf16_f32 v143, v132, v133
	v_lshlrev_b64 v[132:133], 11, v[174:175]
	v_lshl_add_u64 v[134:135], v[134:135], 0, v[132:133]
	global_store_dwordx2 v[134:135], v[142:143], off
	v_or_b32_e32 v134, 0x8000, v136
	v_lshlrev_b32_e32 v184, 2, v134
	s_waitcnt lgkmcnt(0)
	s_barrier
; DI void lds_sync() { wait_lgkm0(); bar_(); }
; DI void phase6(const Params& p, char* smem) {
;     ...
;       for (int tm = 0; tm < 4; ++tm) {
;         char* d = smem + (wn * 32 + r) * 1040 + (wm * 128 + tm * 32 + 4 * hh) * 4;
; #pragma unroll
;         for (int q = 0; q < 4; ++q) *(float4*)(d + 32 * q) = make_float4(acc[tm][tn][4 * q], acc[tm][tn][4 * q + 1], acc[tm][tn][4 * q + 2], acc[tm][tn][4 * q + 3]);
;       }
;       lds_sync();
	ds_write_b128 v202, v[48:51]
	ds_write_b128 v202, v[52:55] offset:32
	ds_write_b128 v202, v[56:59] offset:64
	ds_write_b128 v202, v[60:63] offset:96
	ds_write_b128 v202, v[32:35] offset:128
	ds_write_b128 v202, v[36:39] offset:160
	ds_write_b128 v202, v[40:43] offset:192
	ds_write_b128 v202, v[44:47] offset:224
	ds_write_b128 v202, v[16:19] offset:256
	ds_write_b128 v202, v[20:23] offset:288
	ds_write_b128 v202, v[24:27] offset:320
	ds_write_b128 v202, v[28:31] offset:352
	ds_write_b128 v202, v[0:3] offset:384
	ds_write_b128 v202, v[4:7] offset:416
	ds_write_b128 v202, v[8:11] offset:448
	ds_write_b128 v202, v[12:15] offset:480
	v_lshl_add_u64 v[0:1], s[16:17], 0, v[184:185]
	v_lshl_add_u64 v[2:3], v[0:1], 0, v[68:69]
	s_waitcnt lgkmcnt(0)
	s_barrier
; DI unsigned pk_bf16(float lo, float hi) { f32x2v v = {lo, hi}; bf16x2v b = __builtin_convertvector(v, bf16x2v); return __builtin_bit_cast(unsigned, b); }
; DI void phase6(const Params& p, char* smem) {
;     ...
; #pragma unroll
;       for (int hb = 0; hb < 2; ++hb) {
;         float4 xv[8];
; #pragma unroll
;         for (int i = 0; i < 8; ++i) {
;           const int row = r0 + 8 * (hb * 8 + i);
;           xv[i] = *(const float4*)(p.x + obase + (size_t)((row >> 5) * 64 + (row & 31)) * DM);
;         }
; #pragma unroll
;         for (int i = 0; i < 8; ++i) {
;           const int row = r0 + 8 * (hb * 8 + i);
;           const float4 a = *(const float4*)(smem + row * 1040 + ch * 16);
;           uint2 ob; ob.x = pk_bf16(xv[i].x + g.x * a.x, xv[i].y + g.y * a.y); ob.y = pk_bf16(xv[i].z + g.z * a.z, xv[i].w + g.w * a.w);
;           *(uint2*)(p.x1b + obase + (size_t)((row >> 5) * 64 + (row & 31)) * DM) = ob;
;         }
;       }
	global_load_dwordx4 v[2:5], v[2:3], off
	v_lshl_add_u64 v[6:7], v[0:1], 0, v[70:71]
	global_load_dwordx4 v[6:9], v[6:7], off
	v_lshl_add_u64 v[10:11], v[0:1], 0, v[72:73]
	global_load_dwordx4 v[10:13], v[10:11], off
	v_lshl_add_u64 v[14:15], v[0:1], 0, v[74:75]
	global_load_dwordx4 v[14:17], v[14:15], off
	v_lshl_add_u64 v[18:19], v[0:1], 0, v[76:77]
	global_load_dwordx4 v[18:21], v[18:19], off
	v_lshl_add_u64 v[22:23], v[0:1], 0, v[78:79]
	global_load_dwordx4 v[22:25], v[22:23], off
	v_lshl_add_u64 v[26:27], v[0:1], 0, v[80:81]
	global_load_dwordx4 v[26:29], v[26:27], off
	v_lshl_add_u64 v[30:31], v[0:1], 0, v[82:83]
	global_load_dwordx4 v[30:33], v[30:31], off
	ds_read_b128 v[34:37], v128
	ds_read_b128 v[38:41], v128 offset:8320
	v_lshlrev_b32_e32 v184, 1, v134
	v_lshl_add_u64 v[42:43], s[18:19], 0, v[184:185]
	s_waitcnt vmcnt(7) lgkmcnt(1)
	v_pk_fma_f32 v[2:3], v[64:65], v[34:35], v[2:3]
	s_nop 0
	v_cvt_pk_bf16_f32 v34, v2, v3
	v_pk_fma_f32 v[2:3], v[66:67], v[36:37], v[4:5]
	v_lshl_add_u64 v[36:37], v[42:43], 0, v[84:85]
	v_cvt_pk_bf16_f32 v35, v2, v3
	s_waitcnt vmcnt(6) lgkmcnt(0)
	v_pk_fma_f32 v[2:3], v[64:65], v[38:39], v[6:7]
	v_pk_fma_f32 v[6:7], v[66:67], v[40:41], v[8:9]
	v_cvt_pk_bf16_f32 v38, v2, v3
	ds_read_b128 v[2:5], v128 offset:16640
	v_cvt_pk_bf16_f32 v39, v6, v7
	ds_read_b128 v[6:9], v128 offset:24960
	v_lshl_add_u64 v[40:41], v[42:43], 0, v[86:87]
	s_waitcnt vmcnt(5) lgkmcnt(1)
	v_pk_fma_f32 v[2:3], v[64:65], v[2:3], v[10:11]
	s_nop 0
	v_cvt_pk_bf16_f32 v10, v2, v3
	v_pk_fma_f32 v[2:3], v[66:67], v[4:5], v[12:13]
	v_lshl_add_u64 v[12:13], v[42:43], 0, v[88:89]
	v_cvt_pk_bf16_f32 v11, v2, v3
	s_waitcnt vmcnt(4) lgkmcnt(0)
	v_pk_fma_f32 v[2:3], v[64:65], v[6:7], v[14:15]
	v_pk_fma_f32 v[6:7], v[66:67], v[8:9], v[16:17]
	v_cvt_pk_bf16_f32 v14, v2, v3
	ds_read_b128 v[2:5], v128 offset:33280
	v_cvt_pk_bf16_f32 v15, v6, v7
	ds_read_b128 v[6:9], v128 offset:41600
	v_lshl_add_u64 v[16:17], v[42:43], 0, v[90:91]
	s_waitcnt vmcnt(3) lgkmcnt(1)
	v_pk_fma_f32 v[2:3], v[64:65], v[2:3], v[18:19]
	s_nop 0
	v_cvt_pk_bf16_f32 v18, v2, v3
	v_pk_fma_f32 v[2:3], v[66:67], v[4:5], v[20:21]
	v_lshl_add_u64 v[20:21], v[42:43], 0, v[92:93]
	v_cvt_pk_bf16_f32 v19, v2, v3
	s_waitcnt vmcnt(2) lgkmcnt(0)
	v_pk_fma_f32 v[2:3], v[64:65], v[6:7], v[22:23]
	v_pk_fma_f32 v[6:7], v[66:67], v[8:9], v[24:25]
	v_cvt_pk_bf16_f32 v22, v2, v3
	ds_read_b128 v[2:5], v128 offset:49920
	v_cvt_pk_bf16_f32 v23, v6, v7
	ds_read_b128 v[6:9], v128 offset:58240
	v_lshl_add_u64 v[24:25], v[42:43], 0, v[94:95]
	s_waitcnt vmcnt(1) lgkmcnt(1)
	v_pk_fma_f32 v[2:3], v[64:65], v[2:3], v[26:27]
	v_pk_fma_f32 v[4:5], v[66:67], v[4:5], v[28:29]
	v_cvt_pk_bf16_f32 v2, v2, v3
	v_cvt_pk_bf16_f32 v3, v4, v5
	v_lshl_add_u64 v[4:5], v[42:43], 0, v[96:97]
	s_waitcnt vmcnt(0) lgkmcnt(0)
	v_pk_fma_f32 v[6:7], v[64:65], v[6:7], v[30:31]
	global_store_dwordx2 v[36:37], v[34:35], off
	global_store_dwordx2 v[40:41], v[38:39], off
	global_store_dwordx2 v[12:13], v[10:11], off
	global_store_dwordx2 v[16:17], v[14:15], off
	global_store_dwordx2 v[20:21], v[18:19], off
	global_store_dwordx2 v[24:25], v[22:23], off
	global_store_dwordx2 v[4:5], v[2:3], off
	v_pk_fma_f32 v[2:3], v[66:67], v[8:9], v[32:33]
	v_cvt_pk_bf16_f32 v6, v6, v7
	v_cvt_pk_bf16_f32 v7, v2, v3
	v_lshl_add_u64 v[2:3], v[42:43], 0, v[98:99]
	global_store_dwordx2 v[2:3], v[6:7], off
	v_lshl_add_u64 v[2:3], v[0:1], 0, v[100:101]
	global_load_dwordx4 v[2:5], v[2:3], off
	v_lshl_add_u64 v[6:7], v[0:1], 0, v[102:103]
	global_load_dwordx4 v[6:9], v[6:7], off
	v_lshl_add_u64 v[10:11], v[0:1], 0, v[104:105]
	global_load_dwordx4 v[10:13], v[10:11], off
	v_lshl_add_u64 v[14:15], v[0:1], 0, v[106:107]
	global_load_dwordx4 v[14:17], v[14:15], off
	v_lshl_add_u64 v[18:19], v[0:1], 0, v[108:109]
	global_load_dwordx4 v[18:21], v[18:19], off
	v_lshl_add_u64 v[22:23], v[0:1], 0, v[110:111]
	global_load_dwordx4 v[22:25], v[22:23], off
	v_lshl_add_u64 v[26:27], v[0:1], 0, v[112:113]
	global_load_dwordx4 v[26:29], v[26:27], off
	v_lshl_add_u64 v[0:1], v[0:1], 0, v[114:115]
	global_load_dwordx4 v[30:33], v[0:1], off
	ds_read_b128 v[34:37], v129
	ds_read_b128 v[38:41], v137 offset:58240
	s_waitcnt vmcnt(7) lgkmcnt(1)
	v_pk_fma_f32 v[0:1], v[64:65], v[34:35], v[2:3]
	s_nop 0
	v_cvt_pk_bf16_f32 v34, v0, v1
	v_pk_fma_f32 v[0:1], v[66:67], v[36:37], v[4:5]
	s_waitcnt vmcnt(6) lgkmcnt(0)
	v_pk_fma_f32 v[4:5], v[66:67], v[40:41], v[8:9]
	v_cvt_pk_bf16_f32 v35, v0, v1
	v_pk_fma_f32 v[0:1], v[64:65], v[38:39], v[6:7]
	v_cvt_pk_bf16_f32 v39, v4, v5
	v_cvt_pk_bf16_f32 v38, v0, v1
	ds_read_b128 v[0:3], v186 offset:58240
	ds_read_b128 v[4:7], v187 offset:58240
	v_lshl_add_u64 v[36:37], v[42:43], 0, v[116:117]
	v_lshl_add_u64 v[8:9], v[42:43], 0, v[118:119]
	s_waitcnt vmcnt(5) lgkmcnt(1)
	v_pk_fma_f32 v[0:1], v[64:65], v[0:1], v[10:11]
	s_nop 0
	v_cvt_pk_bf16_f32 v10, v0, v1
	v_pk_fma_f32 v[0:1], v[66:67], v[2:3], v[12:13]
	v_lshl_add_u64 v[12:13], v[42:43], 0, v[120:121]
	v_cvt_pk_bf16_f32 v11, v0, v1
	s_waitcnt vmcnt(4) lgkmcnt(0)
	v_pk_fma_f32 v[0:1], v[64:65], v[4:5], v[14:15]
	v_pk_fma_f32 v[4:5], v[66:67], v[6:7], v[16:17]
	v_cvt_pk_bf16_f32 v14, v0, v1
	ds_read_b128 v[0:3], v188 offset:58240
	v_cvt_pk_bf16_f32 v15, v4, v5
	ds_read_b128 v[4:7], v189 offset:58240
	v_lshl_add_u64 v[16:17], v[42:43], 0, v[122:123]
	s_waitcnt vmcnt(3) lgkmcnt(1)
	v_pk_fma_f32 v[0:1], v[64:65], v[0:1], v[18:19]
	s_nop 0
	v_cvt_pk_bf16_f32 v18, v0, v1
	v_pk_fma_f32 v[0:1], v[66:67], v[2:3], v[20:21]
	v_lshl_add_u64 v[20:21], v[42:43], 0, v[124:125]
	v_cvt_pk_bf16_f32 v19, v0, v1
	s_waitcnt vmcnt(2) lgkmcnt(0)
	v_pk_fma_f32 v[0:1], v[64:65], v[4:5], v[22:23]
	v_pk_fma_f32 v[4:5], v[66:67], v[6:7], v[24:25]
	v_cvt_pk_bf16_f32 v22, v0, v1
	ds_read_b128 v[0:3], v190 offset:58240
	v_cvt_pk_bf16_f32 v23, v4, v5
	ds_read_b128 v[4:7], v191 offset:49920
	v_lshl_add_u64 v[24:25], v[42:43], 0, v[126:127]
	s_waitcnt vmcnt(1) lgkmcnt(1)
	v_pk_fma_f32 v[0:1], v[64:65], v[0:1], v[26:27]
	v_pk_fma_f32 v[2:3], v[66:67], v[2:3], v[28:29]
	v_cvt_pk_bf16_f32 v0, v0, v1
	v_cvt_pk_bf16_f32 v1, v2, v3
	v_lshl_add_u64 v[2:3], v[42:43], 0, v[130:131]
	s_waitcnt vmcnt(0) lgkmcnt(0)
	v_pk_fma_f32 v[4:5], v[64:65], v[4:5], v[30:31]
	global_store_dwordx2 v[36:37], v[34:35], off
	global_store_dwordx2 v[8:9], v[38:39], off
	global_store_dwordx2 v[12:13], v[10:11], off
	global_store_dwordx2 v[16:17], v[14:15], off
	global_store_dwordx2 v[20:21], v[18:19], off
	global_store_dwordx2 v[24:25], v[22:23], off
	global_store_dwordx2 v[2:3], v[0:1], off
	v_pk_fma_f32 v[0:1], v[66:67], v[6:7], v[32:33]
	v_cvt_pk_bf16_f32 v4, v4, v5
	v_cvt_pk_bf16_f32 v5, v0, v1
	v_lshl_add_u64 v[0:1], v[42:43], 0, v[132:133]
	global_store_dwordx2 v[0:1], v[4:5], off
	s_waitcnt lgkmcnt(0)
	s_barrier
	s_cbranch_scc0 .LBB0_929

; DI int tid_() { int t = threadIdx.x; asm volatile("" : "+v"(t)); return t; }
; DI void bar_() { __builtin_amdgcn_s_barrier(); }
; template <int TM, int TN, int WM, int WN, bool SUMSQ, int NST, class AF, class BF, class AFN, class BFN>
; DI void gemm8x(f32x16 (&acc)[TM][TN], AF arow, BF brow, int K, char* smem, float& sumsq, bool pre, bool hasNext, AFN arowN, BFN browN) {
;     ...
;   const int t = tid_(), lane = t & 63, w = t >> 6, r = lane & 31, hh = lane >> 5;
;   const int wm = w % WM, wn = w / WM;
;   const int row0 = t >> 3;
;   const int c = (t & 7) ^ ((row0 >> 1) & 7);
;   const bool a0v = row0 < RA, a1v = row0 + 64 < RA, a2v = row0 + 128 < RA, a3v = row0 + 192 < RA;
;   const bool b0v = row0 < RB, b1v = row0 + 64 < RB, b2v = row0 + 128 < RB, b3v = row0 + 192 < RB;
;   const bf16_t* pa0 = arow(a0v ? row0 : 0) + c * 8;
;   const bf16_t* pa1 = arow(a1v ? row0 + 64 : 0) + c * 8;
;   const bf16_t* pa2 = arow(a2v ? row0 + 128 : 0) + c * 8;
;   const bf16_t* pa3 = arow(a3v ? row0 + 192 : 0) + c * 8;
;   const bf16_t* pb0 = brow(b0v ? row0 : 0) + c * 8;
;   const bf16_t* pb1 = brow(b1v ? row0 + 64 : 0) + c * 8;
;   const bf16_t* pb2 = brow(b2v ? row0 + 128 : 0) + c * 8;
;   const bf16_t* pb3 = brow(b3v ? row0 + 192 : 0) + c * 8;
;   if (!pre) {
;     char* l_ = smem + t * 16; char* m_ = l_ + RA * LDR;
;     if (a0v) GLDS(pa0, l_); if (a1v) GLDS(pa1, l_ + 8192); if (a2v) GLDS(pa2, l_ + 16384); if (a3v) GLDS(pa3, l_ + 24576);
;     if (b0v) GLDS(pb0, m_); if (b1v) GLDS(pb1, m_ + 8192); if (b2v) GLDS(pb2, m_ + 16384); if (b3v) GLDS(pb3, m_ + 24576);
;   }
;   if (NST == 3) {
;     char* l_ = smem + STAGE + t * 16; char* m_ = l_ + RA * LDR;
;     GLDS(pa0 + 64, l_); GLDS(pa1 + 64, l_ + 8192); GLDS(pa2 + 64, l_ + 16384); GLDS(pa3 + 64, l_ + 24576);
;     GLDS(pb0 + 64, m_); GLDS(pb1 + 64, m_ + 8192);
;     asm volatile("s_waitcnt vmcnt(6)" ::: "memory");
;   } else wait_vm0();
;   bar_();
;   const int nk = K >> 6;
;   const int sw = (r >> 1) & 7;
;   const int aoff = (wm * TM * 32 + r) * LDR, boff = RA * LDR + (wn * TN * 32 + r) * LDR;
; DI void phase6(const Params& p, char* smem) {
;     ...
;     f32x16 acc[4][2];
; #pragma unroll
;     for (int a = 0; a < 4; ++a)
; #pragma unroll
;       for (int c = 0; c < 2; ++c) acc[a][c] = zero16();
;     float dummy = 0.f;
;     const bf16_t* Wb = p.WoutT + (size_t)nt * 256 * DM; const bf16_t* Mb = p.m + (size_t)tokTile * 256 * DM;
.LBB0_908:
	s_or_b64 exec, exec, s[28:29]
	v_ashrrev_i32_e32 v10, 6, v9
	v_lshrrev_b32_e32 v12, 31, v9
	v_add_u32_e32 v12, v10, v12
	v_and_b32_e32 v13, 0x3fffe, v12
	v_bfe_u32 v11, v9, 5, 1
	v_sub_u32_e32 v10, v10, v13
	v_lshrrev_b32_e32 v13, 1, v9
	v_bfe_u32 v14, v9, 1, 3
	v_lshlrev_b32_e32 v9, 7, v9
	v_and_b32_e32 v209, 0xf80, v9
	v_lshlrev_b32_e32 v9, 12, v12
	s_lshr_b32 s24, s42, 3
	s_add_i32 s26, s30, s46
	s_and_b32 s27, s31, 7
	v_and_b32_e32 v210, 0xffffe000, v9
	v_bitop3_b32 v9, v13, v11, 7 bitop3:0x6c
	s_and_b32 s24, s24, 3
	s_add_i32 s26, s26, s27
	v_lshlrev_b32_e32 v207, 4, v9
	v_bitop3_b32 v9, v11, v14, 2 bitop3:0x36
	s_lshl_b32 s24, s24, 19
	s_lshl_b32 s26, s26, 19
	s_mov_b32 s27, s25
	v_lshlrev_b32_e32 v206, 4, v9
	v_bitop3_b32 v9, v11, v14, 4 bitop3:0x36
	v_and_b32_e32 v8, 7, v8
	v_lshl_or_b32 v208, v10, 14, v209
	v_lshlrev_b32_e32 v205, 4, v9
	v_bitop3_b32 v9, v11, v14, 6 bitop3:0x36
	v_lshl_add_u64 v[10:11], s[24:25], 0, v[0:1]
	v_lshlrev_b32_e32 v184, 4, v8
	v_lshl_add_u64 v[0:1], s[26:27], 0, v[0:1]
	v_lshl_add_u64 v[0:1], v[0:1], 0, v[184:185]
	v_lshlrev_b32_e32 v204, 4, v9
	v_lshl_add_u64 v[8:9], v[10:11], 0, v[184:185]
	v_lshl_add_u64 v[194:195], s[22:23], 0, v[0:1]
	v_lshl_add_u64 v[0:1], s[26:27], 0, v[2:3]
	v_lshl_add_u64 v[186:187], s[20:21], 0, v[8:9]
	v_lshl_add_u64 v[8:9], s[24:25], 0, v[2:3]
	v_lshl_add_u64 v[0:1], v[0:1], 0, v[184:185]
	v_lshl_add_u64 v[8:9], v[8:9], 0, v[184:185]
	v_lshl_add_u64 v[196:197], s[22:23], 0, v[0:1]
	v_lshl_add_u64 v[0:1], s[26:27], 0, v[4:5]
	v_lshl_add_u64 v[188:189], s[20:21], 0, v[8:9]
	v_lshl_add_u64 v[8:9], s[24:25], 0, v[4:5]
	v_lshl_add_u64 v[0:1], v[0:1], 0, v[184:185]
	v_lshl_add_u64 v[8:9], v[8:9], 0, v[184:185]
	v_lshl_add_u64 v[198:199], s[22:23], 0, v[0:1]
	v_lshl_add_u64 v[0:1], s[26:27], 0, v[6:7]
	s_waitcnt vmcnt(0)
	v_lshl_add_u64 v[190:191], s[20:21], 0, v[8:9]
	v_lshl_add_u64 v[8:9], s[24:25], 0, v[6:7]
	v_lshl_add_u64 v[0:1], v[0:1], 0, v[184:185]
	v_lshl_add_u64 v[8:9], v[8:9], 0, v[184:185]
	v_lshl_add_u64 v[200:201], s[22:23], 0, v[0:1]
	v_mov_b32_e32 v0, 0
	v_or_b32_e32 v211, v209, v210
	v_lshl_add_u64 v[192:193], s[20:21], 0, v[8:9]
	s_mov_b32 s24, 0
	s_mov_b64 s[26:27], 0
	v_mov_b32_e32 v1, v0
	v_mov_b32_e32 v2, v0
	v_mov_b32_e32 v3, v0
	v_mov_b32_e32 v4, v0
	v_mov_b32_e32 v5, v0
	v_mov_b32_e32 v6, v0
	v_mov_b32_e32 v7, v0
	v_mov_b32_e32 v8, v0
	v_mov_b32_e32 v9, v0
	v_mov_b32_e32 v10, v0
	v_mov_b32_e32 v11, v0
	v_mov_b32_e32 v12, v0
	v_mov_b32_e32 v13, v0
	v_mov_b32_e32 v14, v0
	v_mov_b32_e32 v15, v0
	v_mov_b32_e32 v64, v0
	v_mov_b32_e32 v65, v0
	v_mov_b32_e32 v66, v0
	v_mov_b32_e32 v67, v0
	v_mov_b32_e32 v68, v0
	v_mov_b32_e32 v69, v0
	v_mov_b32_e32 v70, v0
	v_mov_b32_e32 v71, v0
	v_mov_b32_e32 v72, v0
	v_mov_b32_e32 v73, v0
	v_mov_b32_e32 v74, v0
	v_mov_b32_e32 v75, v0
	v_mov_b32_e32 v76, v0
	v_mov_b32_e32 v77, v0
	v_mov_b32_e32 v78, v0
	v_mov_b32_e32 v79, v0
	v_mov_b32_e32 v16, v0
	v_mov_b32_e32 v17, v0
	v_mov_b32_e32 v18, v0
	v_mov_b32_e32 v19, v0
	v_mov_b32_e32 v20, v0
	v_mov_b32_e32 v21, v0
	v_mov_b32_e32 v22, v0
	v_mov_b32_e32 v23, v0
	v_mov_b32_e32 v24, v0
	v_mov_b32_e32 v25, v0
	v_mov_b32_e32 v26, v0
	v_mov_b32_e32 v27, v0
	v_mov_b32_e32 v28, v0
	v_mov_b32_e32 v29, v0
	v_mov_b32_e32 v30, v0
	v_mov_b32_e32 v31, v0
	v_mov_b32_e32 v80, v0
	v_mov_b32_e32 v81, v0
	v_mov_b32_e32 v82, v0
	v_mov_b32_e32 v83, v0
	v_mov_b32_e32 v84, v0
	v_mov_b32_e32 v85, v0
	v_mov_b32_e32 v86, v0
	v_mov_b32_e32 v87, v0
	v_mov_b32_e32 v88, v0
	v_mov_b32_e32 v89, v0
	v_mov_b32_e32 v90, v0
	v_mov_b32_e32 v91, v0
	v_mov_b32_e32 v92, v0
	v_mov_b32_e32 v93, v0
	v_mov_b32_e32 v94, v0
	v_mov_b32_e32 v95, v0
	v_mov_b32_e32 v32, v0
	v_mov_b32_e32 v33, v0
	v_mov_b32_e32 v34, v0
	v_mov_b32_e32 v35, v0
	v_mov_b32_e32 v36, v0
	v_mov_b32_e32 v37, v0
	v_mov_b32_e32 v38, v0
	v_mov_b32_e32 v39, v0
	v_mov_b32_e32 v40, v0
	v_mov_b32_e32 v41, v0
	v_mov_b32_e32 v42, v0
	v_mov_b32_e32 v43, v0
	v_mov_b32_e32 v44, v0
	v_mov_b32_e32 v45, v0
	v_mov_b32_e32 v46, v0
	v_mov_b32_e32 v47, v0
	v_mov_b32_e32 v96, v0
	v_mov_b32_e32 v97, v0
	v_mov_b32_e32 v98, v0
	v_mov_b32_e32 v99, v0
	v_mov_b32_e32 v100, v0
	v_mov_b32_e32 v101, v0
	v_mov_b32_e32 v102, v0
	v_mov_b32_e32 v103, v0
	v_mov_b32_e32 v104, v0
	v_mov_b32_e32 v105, v0
	v_mov_b32_e32 v106, v0
	v_mov_b32_e32 v107, v0
	v_mov_b32_e32 v108, v0
	v_mov_b32_e32 v109, v0
	v_mov_b32_e32 v110, v0
	v_mov_b32_e32 v111, v0
	v_mov_b32_e32 v48, v0
	v_mov_b32_e32 v49, v0
	v_mov_b32_e32 v50, v0
	v_mov_b32_e32 v51, v0
	v_mov_b32_e32 v52, v0
	v_mov_b32_e32 v53, v0
	v_mov_b32_e32 v54, v0
	v_mov_b32_e32 v55, v0
	v_mov_b32_e32 v56, v0
	v_mov_b32_e32 v57, v0
	v_mov_b32_e32 v58, v0
	v_mov_b32_e32 v59, v0
	v_mov_b32_e32 v60, v0
	v_mov_b32_e32 v61, v0
	v_mov_b32_e32 v62, v0
	v_mov_b32_e32 v63, v0
	v_mov_b32_e32 v112, v0
	v_mov_b32_e32 v113, v0
	v_mov_b32_e32 v114, v0
	v_mov_b32_e32 v115, v0
	v_mov_b32_e32 v116, v0
	v_mov_b32_e32 v117, v0
	v_mov_b32_e32 v118, v0
	v_mov_b32_e32 v119, v0
	v_mov_b32_e32 v120, v0
	v_mov_b32_e32 v121, v0
	v_mov_b32_e32 v122, v0
	v_mov_b32_e32 v123, v0
	v_mov_b32_e32 v124, v0
	v_mov_b32_e32 v125, v0
	v_mov_b32_e32 v126, v0
	v_mov_b32_e32 v127, v0
	s_barrier
	v_readfirstlane_b32 s51, v203
	s_and_b32 s50, s24, 0x10000
	v_add_u32_e32 v225, s50, v211
	v_add_u32_e32 v224, s50, v208
	s_xor_b32 s50, s50, 0x10000
	s_add_i32 s50, s50, s51
	v_add_u32_e32 v226, v225, v207
	v_add_u32_e32 v227, v224, v207
	ds_read_b128 v[164:167], v226 offset:32768
	ds_read_b128 v[172:175], v227
	ds_read_b128 v[156:159], v226 offset:36864
	ds_read_b128 v[168:171], v227 offset:4096
	ds_read_b128 v[160:163], v227 offset:8192
	ds_read_b128 v[152:155], v227 offset:12288
	s_mov_b32 m0, s50
	v_lshl_add_u64 v[228:229], v[186:187], 0, s[26:27]
	global_load_lds_dwordx4 v[228:229], off
	s_add_u32 m0, s50, 0x2000
	v_lshl_add_u64 v[230:231], v[188:189], 0, s[26:27]
	global_load_lds_dwordx4 v[230:231], off
	s_add_u32 m0, s50, 0x4000
	v_lshl_add_u64 v[228:229], v[190:191], 0, s[26:27]
	global_load_lds_dwordx4 v[228:229], off
	s_add_u32 m0, s50, 0x6000
	v_lshl_add_u64 v[230:231], v[192:193], 0, s[26:27]
	global_load_lds_dwordx4 v[230:231], off
	s_add_u32 m0, s50, 0x8000
	v_lshl_add_u64 v[228:229], v[194:195], 0, s[26:27]
	global_load_lds_dwordx4 v[228:229], off
	s_add_u32 m0, s50, 0xa000
	v_lshl_add_u64 v[230:231], v[196:197], 0, s[26:27]
	global_load_lds_dwordx4 v[230:231], off
	s_add_u32 m0, s50, 0xc000
	v_lshl_add_u64 v[228:229], v[198:199], 0, s[26:27]
	global_load_lds_dwordx4 v[228:229], off
	s_add_u32 m0, s50, 0xe000
	v_lshl_add_u64 v[230:231], v[200:201], 0, s[26:27]
	global_load_lds_dwordx4 v[230:231], off
	s_branch .Lp6_g0
; DI void wait_vm0() { asm volatile("s_waitcnt vmcnt(0)" ::: "memory"); }
; DI void bar_() { __builtin_amdgcn_s_barrier(); }
; #define GLDS(gp, lp) __builtin_amdgcn_global_load_lds((const unsigned*)(gp), (__attribute__((address_space(3))) unsigned*)(lp), 16, 0, 0)
; #define SB_ __builtin_amdgcn_sched_barrier(0)
; #define LOADF(A_, B_, ks) do { const int po_ = (((ks) * 2 + hh) ^ sw) * 16; \
;       _Pragma("unroll") for (int tm = 0; tm < TM; ++tm) A_[tm] = *(const bf16x8*)(As + tm * 32 * LDR + po_); \
;       _Pragma("unroll") for (int tn = 0; tn < TN; ++tn) B_[tn] = *(const bf16x8*)(Bs + tn * 32 * LDR + po_); } while (0)
; template <int TM, int TN, int WM, int WN, bool SUMSQ, int NST, class AF, class BF, class AFN, class BFN>
; DI void gemm8x(f32x16 (&acc)[TM][TN], AF arow, BF brow, int K, char* smem, float& sumsq, bool pre, bool hasNext, AFN arowN, BFN browN) {
;     ...
;   auto compute = [&](const char* cur, char* nxt, bool issue, const bf16_t* q0, const bf16_t* q1, const bf16_t* q2, const bf16_t* q3,
;                      const bf16_t* s0, const bf16_t* s1, const bf16_t* s2, const bf16_t* s3) {
;     const char* As = cur + aoff;
;     const char* Bs = cur + boff;
;     char* l_ = nxt + t * 16; char* m_ = l_ + RA * LDR;
;     bf16x8 a0[TM], b0[TN], a1[TM], b1[TN];
;     ...
;     LOADF(a0, b0, 0);
;     LOADF(a1, b1, 1);
;     SB_;
;     if (issue) { if (a0v) GLDS(q0, l_); if (a1v) GLDS(q1, l_ + 8192); }
;     SB_;
;     __builtin_amdgcn_s_setprio(1);
;     MMF(a0, b0);
;     LOADF(a0, b0, 2);
;     SB_;
;     if (issue) { if (a2v) GLDS(q2, l_ + 16384); if (a3v) GLDS(q3, l_ + 24576); }
;     SB_;
;     MMF(a1, b1);
;     LOADF(a1, b1, 3);
;     SB_;
;     if (issue) { if (b0v) GLDS(s0, m_); if (b1v) GLDS(s1, m_ + 8192); }
;     SB_;
;     MMF(a0, b0);
;     SB_;
;     if (issue) { if (b2v) GLDS(s2, m_ + 16384); if (b3v) GLDS(s3, m_ + 24576); }
;     SB_;
;     MMF(a1, b1);
;     __builtin_amdgcn_s_setprio(0);
;   };
;   int sc_ = 0;
;   for (int kt = 0; kt < nk - 1; ++kt) {
;     SB_;
;     if (NST == 2) {
;       const int ko = (kt + 1) * 64;
;       compute(smem + (kt & 1) * STAGE, smem + ((kt + 1) & 1) * STAGE, true, pa0 + ko, pa1 + ko, pa2 + ko, pa3 + ko, pb0 + ko, pb1 + ko, pb2 + ko, pb3 + ko);
;       SB_;
;       wait_vm0(); bar_();
.Lp6_loop:
	s_and_b32 s50, s24, 0x10000
	v_add_u32_e32 v225, s50, v211
	v_add_u32_e32 v224, s50, v208
	s_xor_b32 s50, s50, 0x10000
	s_add_i32 s50, s50, s51
	v_add_u32_e32 v226, v225, v207
	v_add_u32_e32 v227, v224, v207
	s_setprio 1
	v_mfma_f32_32x32x16_bf16 v[112:127], v[148:151], v[140:143], v[112:127]
	ds_read_b128 v[164:167], v226 offset:32768
	ds_read_b128 v[172:175], v227
	s_mov_b32 m0, s50
	v_lshl_add_u64 v[228:229], v[186:187], 0, s[26:27]
	global_load_lds_dwordx4 v[228:229], off
	v_mfma_f32_32x32x16_bf16 v[48:63], v[148:151], v[132:135], v[48:63]
	ds_read_b128 v[156:159], v226 offset:36864
	ds_read_b128 v[168:171], v227 offset:4096
	s_add_u32 m0, s50, 0x2000
	v_lshl_add_u64 v[230:231], v[188:189], 0, s[26:27]
	global_load_lds_dwordx4 v[230:231], off
	v_mfma_f32_32x32x16_bf16 v[96:111], v[144:147], v[140:143], v[96:111]
	ds_read_b128 v[160:163], v227 offset:8192
	s_add_u32 m0, s50, 0x4000
	v_lshl_add_u64 v[228:229], v[190:191], 0, s[26:27]
	global_load_lds_dwordx4 v[228:229], off
	v_mfma_f32_32x32x16_bf16 v[32:47], v[144:147], v[132:135], v[32:47]
	ds_read_b128 v[152:155], v227 offset:12288
	s_add_u32 m0, s50, 0x6000
	v_lshl_add_u64 v[230:231], v[192:193], 0, s[26:27]
	global_load_lds_dwordx4 v[230:231], off
	v_mfma_f32_32x32x16_bf16 v[80:95], v[136:139], v[140:143], v[80:95]
	s_add_u32 m0, s50, 0x8000
	v_lshl_add_u64 v[228:229], v[194:195], 0, s[26:27]
	global_load_lds_dwordx4 v[228:229], off
	v_mfma_f32_32x32x16_bf16 v[16:31], v[136:139], v[132:135], v[16:31]
	s_add_u32 m0, s50, 0xa000
	v_lshl_add_u64 v[230:231], v[196:197], 0, s[26:27]
	global_load_lds_dwordx4 v[230:231], off
	v_mfma_f32_32x32x16_bf16 v[64:79], v[128:131], v[140:143], v[64:79]
	s_add_u32 m0, s50, 0xc000
	v_lshl_add_u64 v[228:229], v[198:199], 0, s[26:27]
	global_load_lds_dwordx4 v[228:229], off
	v_mfma_f32_32x32x16_bf16 v[0:15], v[128:131], v[132:135], v[0:15]
	s_add_u32 m0, s50, 0xe000
	v_lshl_add_u64 v[230:231], v[200:201], 0, s[26:27]
	global_load_lds_dwordx4 v[230:231], off
.Lp6_g0:
	s_setprio 1
	v_add_u32_e32 v226, v225, v206
	v_add_u32_e32 v227, v224, v206
	s_waitcnt lgkmcnt(0)
	v_mfma_f32_32x32x16_bf16 v[112:127], v[172:175], v[164:167], v[112:127]
	ds_read_b128 v[140:143], v226 offset:32768
	ds_read_b128 v[148:151], v227
	v_mfma_f32_32x32x16_bf16 v[48:63], v[172:175], v[156:159], v[48:63]
	ds_read_b128 v[132:135], v226 offset:36864
	ds_read_b128 v[144:147], v227 offset:4096
	v_mfma_f32_32x32x16_bf16 v[96:111], v[168:171], v[164:167], v[96:111]
	ds_read_b128 v[136:139], v227 offset:8192
	v_mfma_f32_32x32x16_bf16 v[32:47], v[168:171], v[156:159], v[32:47]
	ds_read_b128 v[128:131], v227 offset:12288
	v_mfma_f32_32x32x16_bf16 v[80:95], v[160:163], v[164:167], v[80:95]
	v_mfma_f32_32x32x16_bf16 v[16:31], v[160:163], v[156:159], v[16:31]
	v_mfma_f32_32x32x16_bf16 v[64:79], v[152:155], v[164:167], v[64:79]
	v_mfma_f32_32x32x16_bf16 v[0:15], v[152:155], v[156:159], v[0:15]
	v_add_u32_e32 v226, v225, v205
	v_add_u32_e32 v227, v224, v205
	s_waitcnt lgkmcnt(0)
	v_mfma_f32_32x32x16_bf16 v[112:127], v[148:151], v[140:143], v[112:127]
	ds_read_b128 v[164:167], v226 offset:32768
	ds_read_b128 v[172:175], v227
	v_mfma_f32_32x32x16_bf16 v[48:63], v[148:151], v[132:135], v[48:63]
	ds_read_b128 v[156:159], v226 offset:36864
	ds_read_b128 v[168:171], v227 offset:4096
	v_mfma_f32_32x32x16_bf16 v[96:111], v[144:147], v[140:143], v[96:111]
	ds_read_b128 v[160:163], v227 offset:8192
	v_mfma_f32_32x32x16_bf16 v[32:47], v[144:147], v[132:135], v[32:47]
	ds_read_b128 v[152:155], v227 offset:12288
	v_mfma_f32_32x32x16_bf16 v[80:95], v[136:139], v[140:143], v[80:95]
	v_mfma_f32_32x32x16_bf16 v[16:31], v[136:139], v[132:135], v[16:31]
	v_mfma_f32_32x32x16_bf16 v[64:79], v[128:131], v[140:143], v[64:79]
	v_mfma_f32_32x32x16_bf16 v[0:15], v[128:131], v[132:135], v[0:15]
	v_add_u32_e32 v226, v225, v204
	v_add_u32_e32 v227, v224, v204
	s_waitcnt lgkmcnt(0)
	v_mfma_f32_32x32x16_bf16 v[112:127], v[172:175], v[164:167], v[112:127]
	ds_read_b128 v[140:143], v226 offset:32768
	ds_read_b128 v[148:151], v227
	v_mfma_f32_32x32x16_bf16 v[48:63], v[172:175], v[156:159], v[48:63]
	ds_read_b128 v[132:135], v226 offset:36864
	ds_read_b128 v[144:147], v227 offset:4096
	v_mfma_f32_32x32x16_bf16 v[96:111], v[168:171], v[164:167], v[96:111]
	ds_read_b128 v[136:139], v227 offset:8192
	v_mfma_f32_32x32x16_bf16 v[32:47], v[168:171], v[156:159], v[32:47]
	ds_read_b128 v[128:131], v227 offset:12288
	v_mfma_f32_32x32x16_bf16 v[80:95], v[160:163], v[164:167], v[80:95]
	v_mfma_f32_32x32x16_bf16 v[16:31], v[160:163], v[156:159], v[16:31]
	v_mfma_f32_32x32x16_bf16 v[64:79], v[152:155], v[164:167], v[64:79]
	v_mfma_f32_32x32x16_bf16 v[0:15], v[152:155], v[156:159], v[0:15]
	s_setprio 0
	s_waitcnt vmcnt(0) lgkmcnt(0)
	s_add_i32 s24, s24, 0x10000
	s_add_u32 s26, s26, 0x80
	s_addc_u32 s27, s27, 0
	s_cmpk_eq_i32 s26, 0x780
	s_barrier
; DI void lds_sync() { wait_lgkm0(); bar_(); }
; #define GLDS(gp, lp) __builtin_amdgcn_global_load_lds((const unsigned*)(gp), (__attribute__((address_space(3))) unsigned*)(lp), 16, 0, 0)
; #define SB_ __builtin_amdgcn_sched_barrier(0)
; template <int TM, int TN, int WM, int WN, bool SUMSQ, int NST, class AF, class BF, class AFN, class BFN>
; DI void gemm8x(f32x16 (&acc)[TM][TN], AF arow, BF brow, int K, char* smem, float& sumsq, bool pre, bool hasNext, AFN arowN, BFN browN) {
;     ...
;   auto compute = [&](const char* cur, char* nxt, bool issue, const bf16_t* q0, const bf16_t* q1, const bf16_t* q2, const bf16_t* q3,
;                      const bf16_t* s0, const bf16_t* s1, const bf16_t* s2, const bf16_t* s3) {
;     const char* As = cur + aoff;
;     const char* Bs = cur + boff;
;     char* l_ = nxt + t * 16; char* m_ = l_ + RA * LDR;
;     bf16x8 a0[TM], b0[TN], a1[TM], b1[TN];
;     ...
;     LOADF(a0, b0, 0);
;     LOADF(a1, b1, 1);
;     SB_;
;     if (issue) { if (a0v) GLDS(q0, l_); if (a1v) GLDS(q1, l_ + 8192); }
;     SB_;
;     __builtin_amdgcn_s_setprio(1);
;     MMF(a0, b0);
;     LOADF(a0, b0, 2);
;     SB_;
;     if (issue) { if (a2v) GLDS(q2, l_ + 16384); if (a3v) GLDS(q3, l_ + 24576); }
;     SB_;
;     MMF(a1, b1);
;     LOADF(a1, b1, 3);
;     SB_;
;     if (issue) { if (b0v) GLDS(s0, m_); if (b1v) GLDS(s1, m_ + 8192); }
;     SB_;
;     MMF(a0, b0);
;     SB_;
;     if (issue) { if (b2v) GLDS(s2, m_ + 16384); if (b3v) GLDS(s3, m_ + 24576); }
;     SB_;
;     MMF(a1, b1);
;     __builtin_amdgcn_s_setprio(0);
;     ...
;     const bf16_t *q0 = pa0, *q1 = pa0, *q2 = pa0, *q3 = pa0, *s0 = pa0, *s1 = pa0, *s2 = pa0, *s3 = pa0;
;     if (hasNext) {
;       q0 = arowN(a0v ? row0 : 0) + c * 8; q1 = arowN(a1v ? row0 + 64 : 0) + c * 8; q2 = arowN(a2v ? row0 + 128 : 0) + c * 8; q3 = arowN(a3v ? row0 + 192 : 0) + c * 8;
;       s0 = browN(b0v ? row0 : 0) + c * 8; s1 = browN(b1v ? row0 + 64 : 0) + c * 8; s2 = browN(b2v ? row0 + 128 : 0) + c * 8; s3 = browN(b3v ? row0 + 192 : 0) + c * 8;
;     }
;     SB_;
;     compute(smem + ((nk - 1) & 1) * STAGE, smem, hasNext, q0, q1, q2, q3, s0, s1, s2, s3);
;     SB_;
;     lds_sync();
	s_cbranch_scc0 .Lp6_loop
	s_and_b32 s50, s24, 0x10000
	v_add_u32_e32 v225, s50, v211
	v_add_u32_e32 v224, s50, v208
	s_xor_b32 s50, s50, 0x10000
	s_add_i32 s50, s50, s51
	v_add_u32_e32 v226, v225, v207
	v_add_u32_e32 v227, v224, v207
	s_setprio 1
	v_mfma_f32_32x32x16_bf16 v[112:127], v[148:151], v[140:143], v[112:127]
	ds_read_b128 v[164:167], v226 offset:32768
	ds_read_b128 v[172:175], v227
	v_mfma_f32_32x32x16_bf16 v[48:63], v[148:151], v[132:135], v[48:63]
	ds_read_b128 v[156:159], v226 offset:36864
	ds_read_b128 v[168:171], v227 offset:4096
	v_mfma_f32_32x32x16_bf16 v[96:111], v[144:147], v[140:143], v[96:111]
	ds_read_b128 v[160:163], v227 offset:8192
	v_mfma_f32_32x32x16_bf16 v[32:47], v[144:147], v[132:135], v[32:47]
	ds_read_b128 v[152:155], v227 offset:12288
	v_mfma_f32_32x32x16_bf16 v[80:95], v[136:139], v[140:143], v[80:95]
	v_mfma_f32_32x32x16_bf16 v[16:31], v[136:139], v[132:135], v[16:31]
	v_mfma_f32_32x32x16_bf16 v[64:79], v[128:131], v[140:143], v[64:79]
	v_mfma_f32_32x32x16_bf16 v[0:15], v[128:131], v[132:135], v[0:15]
	s_setprio 1
	v_add_u32_e32 v226, v225, v206
	v_add_u32_e32 v227, v224, v206
	s_waitcnt lgkmcnt(0)
	v_mfma_f32_32x32x16_bf16 v[112:127], v[172:175], v[164:167], v[112:127]
	ds_read_b128 v[140:143], v226 offset:32768
	ds_read_b128 v[148:151], v227
	v_mfma_f32_32x32x16_bf16 v[48:63], v[172:175], v[156:159], v[48:63]
	ds_read_b128 v[132:135], v226 offset:36864
	ds_read_b128 v[144:147], v227 offset:4096
	v_mfma_f32_32x32x16_bf16 v[96:111], v[168:171], v[164:167], v[96:111]
	ds_read_b128 v[136:139], v227 offset:8192
	v_mfma_f32_32x32x16_bf16 v[32:47], v[168:171], v[156:159], v[32:47]
	ds_read_b128 v[128:131], v227 offset:12288
	v_mfma_f32_32x32x16_bf16 v[80:95], v[160:163], v[164:167], v[80:95]
	v_mfma_f32_32x32x16_bf16 v[16:31], v[160:163], v[156:159], v[16:31]
	v_mfma_f32_32x32x16_bf16 v[64:79], v[152:155], v[164:167], v[64:79]
	v_mfma_f32_32x32x16_bf16 v[0:15], v[152:155], v[156:159], v[0:15]
	v_add_u32_e32 v226, v225, v205
	v_add_u32_e32 v227, v224, v205
	s_waitcnt lgkmcnt(0)
	v_mfma_f32_32x32x16_bf16 v[112:127], v[148:151], v[140:143], v[112:127]
	ds_read_b128 v[164:167], v226 offset:32768
	ds_read_b128 v[172:175], v227
	v_mfma_f32_32x32x16_bf16 v[48:63], v[148:151], v[132:135], v[48:63]
	ds_read_b128 v[156:159], v226 offset:36864
	ds_read_b128 v[168:171], v227 offset:4096
	v_mfma_f32_32x32x16_bf16 v[96:111], v[144:147], v[140:143], v[96:111]
	ds_read_b128 v[160:163], v227 offset:8192
	v_mfma_f32_32x32x16_bf16 v[32:47], v[144:147], v[132:135], v[32:47]
	ds_read_b128 v[152:155], v227 offset:12288
	v_mfma_f32_32x32x16_bf16 v[80:95], v[136:139], v[140:143], v[80:95]
	v_mfma_f32_32x32x16_bf16 v[16:31], v[136:139], v[132:135], v[16:31]
	v_mfma_f32_32x32x16_bf16 v[64:79], v[128:131], v[140:143], v[64:79]
	v_mfma_f32_32x32x16_bf16 v[0:15], v[128:131], v[132:135], v[0:15]
	v_add_u32_e32 v226, v225, v204
	v_add_u32_e32 v227, v224, v204
	s_waitcnt lgkmcnt(0)
	v_mfma_f32_32x32x16_bf16 v[112:127], v[172:175], v[164:167], v[112:127]
	ds_read_b128 v[140:143], v226 offset:32768
	ds_read_b128 v[148:151], v227
	v_mfma_f32_32x32x16_bf16 v[48:63], v[172:175], v[156:159], v[48:63]
	ds_read_b128 v[132:135], v226 offset:36864
	ds_read_b128 v[144:147], v227 offset:4096
	v_mfma_f32_32x32x16_bf16 v[96:111], v[168:171], v[164:167], v[96:111]
	ds_read_b128 v[136:139], v227 offset:8192
	v_mfma_f32_32x32x16_bf16 v[32:47], v[168:171], v[156:159], v[32:47]
	ds_read_b128 v[128:131], v227 offset:12288
	v_mfma_f32_32x32x16_bf16 v[80:95], v[160:163], v[164:167], v[80:95]
	v_mfma_f32_32x32x16_bf16 v[16:31], v[160:163], v[156:159], v[16:31]
	v_mfma_f32_32x32x16_bf16 v[64:79], v[152:155], v[164:167], v[64:79]
	v_mfma_f32_32x32x16_bf16 v[0:15], v[152:155], v[156:159], v[0:15]
	s_waitcnt lgkmcnt(0)
	v_mfma_f32_32x32x16_bf16 v[112:127], v[148:151], v[140:143], v[112:127]
	v_mfma_f32_32x32x16_bf16 v[48:63], v[148:151], v[132:135], v[48:63]
	v_mfma_f32_32x32x16_bf16 v[96:111], v[144:147], v[140:143], v[96:111]
	v_mfma_f32_32x32x16_bf16 v[32:47], v[144:147], v[132:135], v[32:47]
	v_mfma_f32_32x32x16_bf16 v[80:95], v[136:139], v[140:143], v[80:95]
	v_mfma_f32_32x32x16_bf16 v[16:31], v[136:139], v[132:135], v[16:31]
	v_mfma_f32_32x32x16_bf16 v[64:79], v[128:131], v[140:143], v[64:79]
	v_mfma_f32_32x32x16_bf16 v[0:15], v[128:131], v[132:135], v[0:15]
	s_lshl_b32 s6, s45, 18
	s_branch .Lp6_cont
